# attention: XCD-wide per-round barrier (per-XCC counter, census count from LDS) to align key sweeps across workgroups; plus final_c8
# baseline (speedup 1.0000x reference)
; __device__ __forceinline__ void attn_phase(const Args& a, unsigned char* lds, int lane, int wave) {
;     ...
;     for (int t = gw; t < TT; t += NGW) {
;         const bool sample = t >= TP; const int bb = sample ? (t - TP) >> 6 : 0;
;         const int c = t >> 6; const int L = sample ? 1088 : 64 * (c + 1);
;         const int nsel = min(256, L);
;         const unsigned* cand = CAND + (size_t)t * 256;
; #pragma unroll
;         for (int j = 0; j < 4; ++j) { const int i = j * 64 + lane; if (i < nsel) sel[i] = cand[i] & 0x3FFFu; }
; __device__ __forceinline__ unsigned xb_ld(unsigned* p)              { return __hip_atomic_load(p, __ATOMIC_RELAXED, __HIP_MEMORY_SCOPE_AGENT); }
; __device__ __forceinline__ unsigned xb_add(unsigned* p, unsigned v) { return __hip_atomic_fetch_add(p, v, __ATOMIC_RELAXED, __HIP_MEMORY_SCOPE_AGENT); }
; __device__ __forceinline__ unsigned xb_xcc_id() { return (unsigned)__builtin_amdgcn_s_getreg((3 << 11) | 20) & 0xFu; }
.Lat_q:
	s_barrier
	s_cmpk_lg_i32 s66, 0x100
	s_cbranch_scc1 .Lat_q_go
	s_lshr_b32 s0, s2, 11
	s_cmp_gt_u32 s0, 7
	s_cbranch_scc1 .Lat_q_go
	s_cmp_lg_u32 s96, 0
	s_cbranch_scc1 .Lat_q_wait
	v_mov_b32_e32 v0, 0x24800
	ds_read_b32 v0, v0
	s_add_i32 s0, s0, 1
	s_lshl_b32 s1, s73, 8
	s_add_u32 s10, s62, 0x5000
	s_addc_u32 s11, s63, 0
	s_add_u32 s10, s10, s1
	s_addc_u32 s11, s11, 0
	v_mov_b32_e32 v1, 0
	v_mov_b32_e32 v2, 1
	s_waitcnt lgkmcnt(0)
	v_readfirstlane_b32 s8, v0
	s_mov_b64 s[12:13], exec
	s_mov_b64 exec, 1
	global_atomic_add v1, v2, s[10:11]
	s_mov_b64 exec, s[12:13]
	s_mul_i32 s8, s8, s0
	s_mov_b32 s14, 0
.Lat_q_spin:
	global_load_dword v3, v1, s[10:11] sc1
	s_add_i32 s14, s14, 1
	s_waitcnt vmcnt(0)
	v_readfirstlane_b32 s9, v3
	s_cmp_ge_u32 s9, s8
	s_cbranch_scc1 .Lat_q_wait
	s_cmpk_gt_u32 s14, 0x800
	s_cbranch_scc1 .Lat_q_wait
	s_sleep 1
	s_branch .Lat_q_spin
